# v26 + NSA K-tile LDS swizzle keyed on (row>>1)&7 so the fragment reads are bank-conflict-free for the ds_read_b128 lane groups
# speedup vs baseline: 1.0042x; 1.0042x over previous
; template <int MODE> __device__ __forceinline__ int pop_tile(unsigned& tiles) { int j; if (MODE == 2) { j = 31 - __builtin_clz(tiles); tiles &= ~(1u << j); } else { j = __builtin_ctz(tiles); tiles &= tiles - 1u; } return j; }
; __device__ __forceinline__ void nsa_unit(int b, int g, int tq, const Args& a, LAS unsigned char* lds, int tid, int wave, int lane, int& nxt) {
;     ...
;     const int wv = __builtin_amdgcn_readfirstlane(tid >> 6);
;     const char* ksrc = (const char*)(KS + (size_t)b * SEQ * 128 + 64 * g) + ((size_t)(8 * wv + (lane >> 3)) * 128 + (((lane & 7) ^ (lane >> 3)) * 8)) * 2;
;     const char* vsrc = (const char*)(VS + (size_t)b * SEQ * 128 + 64 * g) + ((size_t)(8 * wv + (lane >> 3)) * 128 + (((lane & 7) ^ (4 * ((lane >> 4) & 1))) * 8)) * 2;
;     const unsigned kvb0 = (unsigned)(uintptr_t)lds;
;     ...
;     unsigned wt; { const int jlo = max(tq - 8, 0); const unsigned hi = (tq == 31) ? 0xffffffffu : ((1u << (tq + 1)) - 1u); wt = hi & ~((1u << jlo) - 1u); }
;     int j0 = pop_tile<2>(wt), m0 = 2, j1 = -1, m1 = 2;
;     NL_DMA(2, j0, 0);
;     if (wt) { j1 = pop_tile<2>(wt); NL_DMA(2, j1, FBUF); }
.LBB0_886:
	s_and_saveexec_b64 s[4:5], s[2:3]
	v_mov_b32_e32 v0, s79
	ds_write_b32 v0, v168
	s_or_b64 exec, exec, s[4:5]
	s_waitcnt lgkmcnt(0)
	s_barrier
	ds_read_b32 v0, v169
	s_waitcnt lgkmcnt(0)
	v_readfirstlane_b32 s4, v0
	s_lshr_b32 s0, s4, 2
	s_lshl_b32 s0, s0, 5
	s_and_b32 s1, s4, 3
	s_or_b32 s0, s0, s1
	s_and_b32 s1, s33, 7
	s_lshl_b32 s1, s1, 2
	s_or_b32 s0, s0, s1
	s_cmpk_gt_i32 s4, 0x7f
	s_cselect_b32 s4, 0x400, s0
	s_cmpk_gt_i32 s4, 0x3ff
	s_cselect_b64 s[56:57], -1, 0
	s_and_b64 vcc, exec, s[56:57]
	s_cbranch_vccnz .LBB0_885
	v_mov_b32_e32 v86, v214
	s_ashr_i32 s67, s4, 5
	s_bfe_u32 s0, s4, 0x40001
	v_readfirstlane_b32 s5, v86
	s_sub_i32 s38, 31, s67
	s_and_b32 s1, s4, 1
	s_ashr_i32 s5, s5, 6
	s_lshl_b32 s8, s0, 19
	v_bfe_u32 v34, v86, 3, 3
	s_add_u32 s6, s68, s8
	v_lshl_or_b32 v2, s5, 3, v34
	s_addc_u32 s7, s69, 0
	s_lshl_b32 s9, s1, 7
	v_ashrrev_i32_e32 v3, 31, v2
	s_add_u32 s6, s6, s9
	v_lshlrev_b64 v[2:3], 7, v[2:3]
	v_bfe_u32 v0, v86, 4, 3
	v_bitop3_b32 v0, v0, v86, 7 bitop3:0x78
	s_addc_u32 s7, s7, 0
	v_lshl_or_b32 v4, v0, 3, v2
	v_mov_b32_e32 v5, v3
	v_lshl_add_u64 v[160:161], v[4:5], 1, s[6:7]
	s_add_u32 s6, s70, s8
	v_and_b32_e32 v82, 7, v86
	s_addc_u32 s7, s71, 0
	v_bfe_u32 v35, v86, 2, 4
	s_add_u32 s6, s6, s9
	v_bitop3_b32 v0, v35, v82, 4 bitop3:0x6c
	s_addc_u32 s7, s7, 0
	v_lshl_or_b32 v2, v0, 3, v2
	v_lshl_add_u64 v[162:163], v[2:3], 1, s[6:7]
	s_lshl_b32 s6, 2, s38
	v_sub_u32_e64 v0, s38, 8 clamp
	s_add_i32 s6, s6, -1
	s_cmp_gt_u32 s4, 31
	v_readfirstlane_b32 s4, v0
	s_cselect_b32 s15, s6, -1
	s_lshl_b32 s4, -1, s4
	s_and_b32 s4, s15, s4
	s_flbit_i32_b32 s6, s4
	s_xor_b32 s14, s6, 31
	s_lshl_b32 s6, 1, s14
	s_andn2_b32 s4, s4, s6
	s_lshl_b32 s6, s14, 14
	s_or_b32 s44, s6, 0x1000000
	s_lshl_b32 s94, s5, 10
	v_lshl_add_u64 v[2:3], v[160:161], 0, s[44:45]
	s_add_i32 s94, s94, 0
	s_mov_b32 m0, s94
	s_nop 0
	global_load_lds_dwordx4 v[2:3], off
	v_lshl_add_u64 v[2:3], v[162:163], 0, s[44:45]
	s_add_i32 s95, s94, 0x2000
	s_mov_b32 m0, s95
	s_nop 0
	global_load_lds_dwordx4 v[2:3], off
	s_mov_b32 s97, -1
	s_cmp_eq_u32 s4, 0
	s_mov_b32 s39, 0
	s_cbranch_scc1 .LBB0_891
	s_flbit_i32_b32 s5, s4
	s_xor_b32 s97, s5, 31
	s_lshl_b32 s5, 1, s97
	s_andn2_b32 s39, s4, s5
	s_lshl_b32 s4, s97, 14
	s_or_b32 s44, s4, 0x1000000
	v_lshl_add_u64 v[2:3], v[160:161], 0, s[44:45]
	s_add_i32 s4, s94, 0x4000
	s_mov_b32 m0, s4
	s_nop 0
	global_load_lds_dwordx4 v[2:3], off
	v_lshl_add_u64 v[2:3], v[162:163], 0, s[44:45]
	s_add_i32 s4, s94, 0x6000
	s_mov_b32 m0, s4
	s_nop 0
	global_load_lds_dwordx4 v[2:3], off

; #define NL_WAITBAR(n) do { asm volatile("s_waitcnt vmcnt(" #n ") lgkmcnt(0)" ::: "memory"); __builtin_amdgcn_s_barrier(); asm volatile("" ::: "memory"); } while (0)
; __device__ __forceinline__ void nsa_unit(int b, int g, int tq, const Args& a, LAS unsigned char* lds, int tid, int wave, int lane, int& nxt) {
;     ...
;         int kfo[4];
; #pragma unroll
;         for (int s = 0; s < 4; ++s) kfo[s] = (lane & 31) * 128 + ((((2 * s + h) ^ (lane & 7))) << 4);
;         int o0 = 0, o1 = FBUF, o2 = 2 * FBUF;
;         float cfar = tabh[127 + 64]; asm volatile("" : "+v"(cfar));
;     ...
;         NL_WAITBAR(2);
;         {
;             float m = 0.f, l = 0.f; bool first = true; f32x16 oa = {}, ob = {};
.LBB0_945:
	v_lshlrev_b32_e32 v0, 7, v84
	v_bfe_u32 v3, v84, 1, 3
	v_xor_b32_e32 v2, v83, v3
	v_lshl_or_b32 v183, v2, 4, v0
	v_bitop3_b32 v2, v83, v3, 2 bitop3:0x36
	v_lshl_or_b32 v184, v2, 4, v0
	v_mov_b32_e32 v2, s96
	ds_read_b32 v185, v2 offset:764
	v_bitop3_b32 v2, v83, v3, 4 bitop3:0x36
	v_lshl_or_b32 v186, v2, 4, v0
	v_bitop3_b32 v2, v83, v3, 6 bitop3:0x36
	s_waitcnt lgkmcnt(0)
	s_waitcnt vmcnt(2) lgkmcnt(0)
	s_barrier
	v_mov_b32_e32 v14, v1
	v_mov_b32_e32 v15, v1
	v_lshl_or_b32 v187, v2, 4, v0
	v_mov_b32_e32 v0, v1
	v_mov_b32_e32 v2, v1
	v_mov_b32_e32 v3, v1
	v_mov_b32_e32 v4, v1
	v_mov_b32_e32 v5, v1
	v_mov_b32_e32 v6, v1
	v_mov_b32_e32 v7, v1
	v_mov_b32_e32 v8, v1
	v_mov_b32_e32 v9, v1
	v_mov_b32_e32 v10, v1
	v_mov_b32_e32 v11, v1
	v_mov_b32_e32 v12, v1
	v_mov_b32_e32 v13, v1
	v_mov_b64_e32 v[78:79], v[14:15]
	v_mov_b64_e32 v[62:63], v[14:15]
	v_add_u32_e32 v188, 0, v128
	s_mov_b32 s50, 0
	s_movk_i32 s51, 0x4000
	s_mov_b32 s4, 0x8000
	v_mov_b32_e32 v167, 0
	s_mov_b64 s[62:63], -1
	v_mov_b64_e32 v[76:77], v[12:13]
	v_mov_b64_e32 v[74:75], v[10:11]
	v_mov_b64_e32 v[72:73], v[8:9]
	v_mov_b64_e32 v[70:71], v[6:7]
	v_mov_b64_e32 v[68:69], v[4:5]
	v_mov_b64_e32 v[66:67], v[2:3]
	v_mov_b64_e32 v[64:65], v[0:1]
	v_mov_b64_e32 v[60:61], v[12:13]
	v_mov_b64_e32 v[58:59], v[10:11]
	v_mov_b64_e32 v[56:57], v[8:9]
	v_mov_b64_e32 v[54:55], v[6:7]
	v_mov_b64_e32 v[52:53], v[4:5]
	v_mov_b64_e32 v[50:51], v[2:3]
	v_mov_b64_e32 v[48:49], v[0:1]
	v_mov_b32_e32 v0, 0
